# v31 + final FFN-out epilogue: 15 later bf16 residual loads issued right after the first into private quads, vmcnt(0) waits replaced by counted waits
# baseline (speedup 1.0000x reference)
.LBB0_2047:
	v_lshl_add_u32 v144, s51, 8, v154
	v_lshl_or_b32 v148, s53, 8, v156
	v_ashrrev_i32_e32 v145, 31, v144
	v_ashrrev_i32_e32 v149, 31, v148
	v_lshlrev_b64 v[146:147], 11, v[144:145]
	v_lshl_add_u64 v[146:147], v[146:147], 0, v[148:149]
	v_lshl_add_u64 v[150:151], v[146:147], 1, s[60:61]
	global_load_dwordx4 v[162:165], v[150:151], off
	global_load_dwordx4 v[168:171], v[150:151], off offset:256
	v_or_b32_e32 v232, 16, v144
	v_ashrrev_i32_e32 v233, 31, v232
	v_lshlrev_b64 v[232:233], 11, v[232:233]
	v_lshl_add_u64 v[232:233], v[232:233], 0, v[148:149]
	v_lshl_add_u64 v[232:233], v[232:233], 1, s[60:61]
	global_load_dwordx4 v[172:175], v[232:233], off
	global_load_dwordx4 v[176:179], v[232:233], off offset:256
	v_or_b32_e32 v232, 32, v144
	v_ashrrev_i32_e32 v233, 31, v232
	v_lshlrev_b64 v[232:233], 11, v[232:233]
	v_lshl_add_u64 v[232:233], v[232:233], 0, v[148:149]
	v_lshl_add_u64 v[232:233], v[232:233], 1, s[60:61]
	global_load_dwordx4 v[180:183], v[232:233], off
	global_load_dwordx4 v[184:187], v[232:233], off offset:256
	v_or_b32_e32 v232, 48, v144
	v_ashrrev_i32_e32 v233, 31, v232
	v_lshlrev_b64 v[232:233], 11, v[232:233]
	v_lshl_add_u64 v[232:233], v[232:233], 0, v[148:149]
	v_lshl_add_u64 v[232:233], v[232:233], 1, s[60:61]
	global_load_dwordx4 v[188:191], v[232:233], off
	global_load_dwordx4 v[192:195], v[232:233], off offset:256
	v_lshl_add_u64 v[232:233], v[146:147], 0, s[20:21]
	v_lshl_add_u64 v[232:233], v[232:233], 1, s[60:61]
	global_load_dwordx4 v[196:199], v[232:233], off
	global_load_dwordx4 v[200:203], v[232:233], off offset:256
	v_lshl_add_u64 v[232:233], v[146:147], 0, s[22:23]
	v_lshl_add_u64 v[232:233], v[232:233], 1, s[60:61]
	global_load_dwordx4 v[204:207], v[232:233], off
	global_load_dwordx4 v[208:211], v[232:233], off offset:256
	v_lshl_add_u64 v[232:233], v[146:147], 0, s[24:25]
	v_lshl_add_u64 v[232:233], v[232:233], 1, s[60:61]
	global_load_dwordx4 v[212:215], v[232:233], off
	global_load_dwordx4 v[216:219], v[232:233], off offset:256
	v_lshl_add_u64 v[232:233], v[146:147], 0, s[26:27]
	v_lshl_add_u64 v[232:233], v[232:233], 1, s[60:61]
	global_load_dwordx4 v[220:223], v[232:233], off
	global_load_dwordx4 v[224:227], v[232:233], off offset:256
	v_cndmask_b32_e64 v152, 0, 1, s[18:19]
	v_cmp_ne_u32_e64 s[4:5], 1, v152
	s_mov_b64 s[6:7], -1
	s_andn2_b64 vcc, exec, s[18:19]
	s_waitcnt vmcnt(15)
	v_lshlrev_b32_e32 v152, 16, v162
	v_and_b32_e32 v153, 0xffff0000, v162
	v_lshlrev_b32_e32 v162, 16, v163
	v_and_b32_e32 v163, 0xffff0000, v163
	v_lshlrev_b32_e32 v166, 16, v164
	v_and_b32_e32 v167, 0xffff0000, v164
	v_lshlrev_b32_e32 v164, 16, v165
	v_and_b32_e32 v165, 0xffff0000, v165
	v_pk_fma_f32 v[126:127], v[126:127], 0.5, v[162:163] op_sel_hi:[1,0,1]
	v_pk_fma_f32 v[124:125], v[124:125], 0.5, v[152:153] op_sel_hi:[1,0,1]
	v_pk_fma_f32 v[122:123], v[122:123], 0.5, v[164:165] op_sel_hi:[1,0,1]
	v_pk_fma_f32 v[120:121], v[120:121], 0.5, v[166:167] op_sel_hi:[1,0,1]
	v_lshl_add_u64 v[152:153], v[146:147], 2, s[86:87]
	s_cbranch_vccnz .LBB0_2049
	s_mov_b64 s[6:7], 0
	global_store_dwordx4 v[152:153], v[124:127], off
	global_store_dwordx4 v[152:153], v[120:123], off offset:16

.LBB0_2051:
	s_and_b64 vcc, exec, s[4:5]
	s_mov_b64 s[6:7], -1
	s_waitcnt vmcnt(14)
	v_lshlrev_b32_e32 v124, 16, v168
	v_and_b32_e32 v125, 0xffff0000, v168
	v_lshlrev_b32_e32 v120, 16, v169
	v_and_b32_e32 v121, 0xffff0000, v169
	v_lshlrev_b32_e32 v126, 16, v170
	v_and_b32_e32 v127, 0xffff0000, v170
	v_lshlrev_b32_e32 v122, 16, v171
	v_and_b32_e32 v123, 0xffff0000, v171
	v_pk_fma_f32 v[118:119], v[118:119], 0.5, v[120:121] op_sel_hi:[1,0,1]
	v_pk_fma_f32 v[116:117], v[116:117], 0.5, v[124:125] op_sel_hi:[1,0,1]
	v_pk_fma_f32 v[114:115], v[114:115], 0.5, v[122:123] op_sel_hi:[1,0,1]
	v_pk_fma_f32 v[112:113], v[112:113], 0.5, v[126:127] op_sel_hi:[1,0,1]
	s_cbranch_vccnz .LBB0_2054
	global_store_dwordx4 v[152:153], v[116:119], off offset:512
	global_store_dwordx4 v[152:153], v[112:115], off offset:528
	s_cbranch_execz .LBB0_2055

.LBB0_2059:
	v_or_b32_e32 v112, 16, v144
	s_waitcnt lgkmcnt(0)
	v_ashrrev_i32_e32 v113, 31, v112
	v_lshlrev_b64 v[112:113], 11, v[112:113]
	v_lshl_add_u64 v[118:119], v[112:113], 0, v[148:149]
	v_lshl_add_u64 v[112:113], v[118:119], 1, s[60:61]
	s_mov_b64 s[34:35], -1
	s_and_b64 vcc, exec, s[4:5]
	s_waitcnt vmcnt(13)
	v_lshlrev_b32_e32 v120, 16, v172
	v_and_b32_e32 v121, 0xffff0000, v172
	v_lshlrev_b32_e32 v114, 16, v173
	v_and_b32_e32 v115, 0xffff0000, v173
	v_lshlrev_b32_e32 v122, 16, v174
	v_and_b32_e32 v123, 0xffff0000, v174
	v_lshlrev_b32_e32 v116, 16, v175
	v_and_b32_e32 v117, 0xffff0000, v175
	v_pk_fma_f32 v[110:111], v[110:111], 0.5, v[114:115] op_sel_hi:[1,0,1]
	v_pk_fma_f32 v[108:109], v[108:109], 0.5, v[120:121] op_sel_hi:[1,0,1]
	v_pk_fma_f32 v[106:107], v[106:107], 0.5, v[116:117] op_sel_hi:[1,0,1]
	v_pk_fma_f32 v[104:105], v[104:105], 0.5, v[122:123] op_sel_hi:[1,0,1]
	v_lshl_add_u64 v[114:115], v[118:119], 2, s[86:87]
	s_cbranch_vccnz .LBB0_2061
	s_mov_b64 s[34:35], 0
	global_store_dwordx4 v[114:115], v[108:111], off
	global_store_dwordx4 v[114:115], v[104:107], off offset:16

.LBB0_2063:
	s_and_b64 vcc, exec, s[4:5]
	s_mov_b64 s[34:35], -1
	s_waitcnt vmcnt(12)
	v_lshlrev_b32_e32 v108, 16, v176
	v_and_b32_e32 v109, 0xffff0000, v176
	v_lshlrev_b32_e32 v104, 16, v177
	v_and_b32_e32 v105, 0xffff0000, v177
	v_lshlrev_b32_e32 v110, 16, v178
	v_and_b32_e32 v111, 0xffff0000, v178
	v_lshlrev_b32_e32 v106, 16, v179
	v_and_b32_e32 v107, 0xffff0000, v179
	v_pk_fma_f32 v[102:103], v[102:103], 0.5, v[104:105] op_sel_hi:[1,0,1]
	v_pk_fma_f32 v[100:101], v[100:101], 0.5, v[108:109] op_sel_hi:[1,0,1]
	v_pk_fma_f32 v[98:99], v[98:99], 0.5, v[106:107] op_sel_hi:[1,0,1]
	v_pk_fma_f32 v[96:97], v[96:97], 0.5, v[110:111] op_sel_hi:[1,0,1]
	s_cbranch_vccnz .LBB0_2066
	global_store_dwordx4 v[114:115], v[100:103], off offset:512
	global_store_dwordx4 v[114:115], v[96:99], off offset:528
	s_cbranch_execz .LBB0_2067

.LBB0_2071:
	v_or_b32_e32 v96, 32, v144
	s_waitcnt lgkmcnt(0)
	v_ashrrev_i32_e32 v97, 31, v96
	v_lshlrev_b64 v[96:97], 11, v[96:97]
	v_lshl_add_u64 v[102:103], v[96:97], 0, v[148:149]
	v_lshl_add_u64 v[96:97], v[102:103], 1, s[60:61]
	s_mov_b64 s[34:35], -1
	s_and_b64 vcc, exec, s[4:5]
	s_waitcnt vmcnt(11)
	v_lshlrev_b32_e32 v104, 16, v180
	v_and_b32_e32 v105, 0xffff0000, v180
	v_lshlrev_b32_e32 v98, 16, v181
	v_and_b32_e32 v99, 0xffff0000, v181
	v_lshlrev_b32_e32 v106, 16, v182
	v_and_b32_e32 v107, 0xffff0000, v182
	v_lshlrev_b32_e32 v100, 16, v183
	v_and_b32_e32 v101, 0xffff0000, v183
	v_pk_fma_f32 v[94:95], v[94:95], 0.5, v[98:99] op_sel_hi:[1,0,1]
	v_pk_fma_f32 v[92:93], v[92:93], 0.5, v[104:105] op_sel_hi:[1,0,1]
	v_pk_fma_f32 v[90:91], v[90:91], 0.5, v[100:101] op_sel_hi:[1,0,1]
	v_pk_fma_f32 v[88:89], v[88:89], 0.5, v[106:107] op_sel_hi:[1,0,1]
	v_lshl_add_u64 v[98:99], v[102:103], 2, s[86:87]
	s_cbranch_vccnz .LBB0_2073
	s_mov_b64 s[34:35], 0
	global_store_dwordx4 v[98:99], v[92:95], off
	global_store_dwordx4 v[98:99], v[88:91], off offset:16

.LBB0_2075:
	s_and_b64 vcc, exec, s[4:5]
	s_mov_b64 s[34:35], -1
	s_waitcnt vmcnt(10)
	v_lshlrev_b32_e32 v92, 16, v184
	v_and_b32_e32 v93, 0xffff0000, v184
	v_lshlrev_b32_e32 v88, 16, v185
	v_and_b32_e32 v89, 0xffff0000, v185
	v_lshlrev_b32_e32 v94, 16, v186
	v_and_b32_e32 v95, 0xffff0000, v186
	v_lshlrev_b32_e32 v90, 16, v187
	v_and_b32_e32 v91, 0xffff0000, v187
	v_pk_fma_f32 v[86:87], v[86:87], 0.5, v[88:89] op_sel_hi:[1,0,1]
	v_pk_fma_f32 v[84:85], v[84:85], 0.5, v[92:93] op_sel_hi:[1,0,1]
	v_pk_fma_f32 v[82:83], v[82:83], 0.5, v[90:91] op_sel_hi:[1,0,1]
	v_pk_fma_f32 v[80:81], v[80:81], 0.5, v[94:95] op_sel_hi:[1,0,1]
	s_cbranch_vccnz .LBB0_2078
	global_store_dwordx4 v[98:99], v[84:87], off offset:512
	global_store_dwordx4 v[98:99], v[80:83], off offset:528
	s_cbranch_execz .LBB0_2079

.LBB0_2083:
	v_or_b32_e32 v80, 48, v144
	s_waitcnt lgkmcnt(0)
	v_ashrrev_i32_e32 v81, 31, v80
	v_lshlrev_b64 v[80:81], 11, v[80:81]
	v_lshl_add_u64 v[86:87], v[80:81], 0, v[148:149]
	v_lshl_add_u64 v[80:81], v[86:87], 1, s[60:61]
	s_mov_b64 s[34:35], -1
	s_and_b64 vcc, exec, s[4:5]
	s_waitcnt vmcnt(9)
	v_lshlrev_b32_e32 v88, 16, v188
	v_and_b32_e32 v89, 0xffff0000, v188
	v_lshlrev_b32_e32 v82, 16, v189
	v_and_b32_e32 v83, 0xffff0000, v189
	v_lshlrev_b32_e32 v90, 16, v190
	v_and_b32_e32 v91, 0xffff0000, v190
	v_lshlrev_b32_e32 v84, 16, v191
	v_and_b32_e32 v85, 0xffff0000, v191
	v_pk_fma_f32 v[78:79], v[78:79], 0.5, v[82:83] op_sel_hi:[1,0,1]
	v_pk_fma_f32 v[76:77], v[76:77], 0.5, v[88:89] op_sel_hi:[1,0,1]
	v_pk_fma_f32 v[74:75], v[74:75], 0.5, v[84:85] op_sel_hi:[1,0,1]
	v_pk_fma_f32 v[72:73], v[72:73], 0.5, v[90:91] op_sel_hi:[1,0,1]
	v_lshl_add_u64 v[82:83], v[86:87], 2, s[86:87]
	s_cbranch_vccnz .LBB0_2085
	s_mov_b64 s[34:35], 0
	global_store_dwordx4 v[82:83], v[76:79], off
	global_store_dwordx4 v[82:83], v[72:75], off offset:16

.LBB0_2087:
	s_and_b64 vcc, exec, s[4:5]
	s_mov_b64 s[34:35], -1
	s_waitcnt vmcnt(8)
	v_lshlrev_b32_e32 v76, 16, v192
	v_and_b32_e32 v77, 0xffff0000, v192
	v_lshlrev_b32_e32 v72, 16, v193
	v_and_b32_e32 v73, 0xffff0000, v193
	v_lshlrev_b32_e32 v78, 16, v194
	v_and_b32_e32 v79, 0xffff0000, v194
	v_lshlrev_b32_e32 v74, 16, v195
	v_and_b32_e32 v75, 0xffff0000, v195
	v_pk_fma_f32 v[70:71], v[70:71], 0.5, v[72:73] op_sel_hi:[1,0,1]
	v_pk_fma_f32 v[68:69], v[68:69], 0.5, v[76:77] op_sel_hi:[1,0,1]
	v_pk_fma_f32 v[66:67], v[66:67], 0.5, v[74:75] op_sel_hi:[1,0,1]
	v_pk_fma_f32 v[64:65], v[64:65], 0.5, v[78:79] op_sel_hi:[1,0,1]
	s_cbranch_vccnz .LBB0_2090
	global_store_dwordx4 v[82:83], v[68:71], off offset:512
	global_store_dwordx4 v[82:83], v[64:67], off offset:528
	s_cbranch_execz .LBB0_2091

.LBB0_2095:
	v_lshl_add_u64 v[70:71], v[146:147], 0, s[20:21]
	s_waitcnt lgkmcnt(0)
	v_lshl_add_u64 v[64:65], v[70:71], 1, s[60:61]
	s_mov_b64 s[34:35], -1
	s_and_b64 vcc, exec, s[4:5]
	s_waitcnt vmcnt(7)
	v_lshlrev_b32_e32 v72, 16, v196
	v_and_b32_e32 v73, 0xffff0000, v196
	v_lshlrev_b32_e32 v66, 16, v197
	v_and_b32_e32 v67, 0xffff0000, v197
	v_lshlrev_b32_e32 v74, 16, v198
	v_and_b32_e32 v75, 0xffff0000, v198
	v_lshlrev_b32_e32 v68, 16, v199
	v_and_b32_e32 v69, 0xffff0000, v199
	v_pk_fma_f32 v[62:63], v[62:63], 0.5, v[66:67] op_sel_hi:[1,0,1]
	v_pk_fma_f32 v[60:61], v[60:61], 0.5, v[72:73] op_sel_hi:[1,0,1]
	v_pk_fma_f32 v[58:59], v[58:59], 0.5, v[68:69] op_sel_hi:[1,0,1]
	v_pk_fma_f32 v[56:57], v[56:57], 0.5, v[74:75] op_sel_hi:[1,0,1]
	v_lshl_add_u64 v[66:67], v[70:71], 2, s[86:87]
	s_cbranch_vccnz .LBB0_2097
	s_mov_b64 s[34:35], 0
	global_store_dwordx4 v[66:67], v[60:63], off
	global_store_dwordx4 v[66:67], v[56:59], off offset:16

.LBB0_2099:
	s_and_b64 vcc, exec, s[4:5]
	s_mov_b64 s[34:35], -1
	s_waitcnt vmcnt(6)
	v_lshlrev_b32_e32 v60, 16, v200
	v_and_b32_e32 v61, 0xffff0000, v200
	v_lshlrev_b32_e32 v56, 16, v201
	v_and_b32_e32 v57, 0xffff0000, v201
	v_lshlrev_b32_e32 v62, 16, v202
	v_and_b32_e32 v63, 0xffff0000, v202
	v_lshlrev_b32_e32 v58, 16, v203
	v_and_b32_e32 v59, 0xffff0000, v203
	v_pk_fma_f32 v[54:55], v[54:55], 0.5, v[56:57] op_sel_hi:[1,0,1]
	v_pk_fma_f32 v[52:53], v[52:53], 0.5, v[60:61] op_sel_hi:[1,0,1]
	v_pk_fma_f32 v[50:51], v[50:51], 0.5, v[58:59] op_sel_hi:[1,0,1]
	v_pk_fma_f32 v[48:49], v[48:49], 0.5, v[62:63] op_sel_hi:[1,0,1]
	s_cbranch_vccnz .LBB0_2102
	global_store_dwordx4 v[66:67], v[52:55], off offset:512
	global_store_dwordx4 v[66:67], v[48:51], off offset:528
	s_cbranch_execz .LBB0_2103

.LBB0_2107:
	v_lshl_add_u64 v[54:55], v[146:147], 0, s[22:23]
	s_waitcnt lgkmcnt(0)
	v_lshl_add_u64 v[48:49], v[54:55], 1, s[60:61]
	s_mov_b64 s[34:35], -1
	s_and_b64 vcc, exec, s[4:5]
	s_waitcnt vmcnt(5)
	v_lshlrev_b32_e32 v56, 16, v204
	v_and_b32_e32 v57, 0xffff0000, v204
	v_lshlrev_b32_e32 v50, 16, v205
	v_and_b32_e32 v51, 0xffff0000, v205
	v_lshlrev_b32_e32 v58, 16, v206
	v_and_b32_e32 v59, 0xffff0000, v206
	v_lshlrev_b32_e32 v52, 16, v207
	v_and_b32_e32 v53, 0xffff0000, v207
	v_pk_fma_f32 v[46:47], v[46:47], 0.5, v[50:51] op_sel_hi:[1,0,1]
	v_pk_fma_f32 v[44:45], v[44:45], 0.5, v[56:57] op_sel_hi:[1,0,1]
	v_pk_fma_f32 v[42:43], v[42:43], 0.5, v[52:53] op_sel_hi:[1,0,1]
	v_pk_fma_f32 v[40:41], v[40:41], 0.5, v[58:59] op_sel_hi:[1,0,1]
	v_lshl_add_u64 v[50:51], v[54:55], 2, s[86:87]
	s_cbranch_vccnz .LBB0_2109
	s_mov_b64 s[34:35], 0
	global_store_dwordx4 v[50:51], v[44:47], off
	global_store_dwordx4 v[50:51], v[40:43], off offset:16

.LBB0_2111:
	s_and_b64 vcc, exec, s[4:5]
	s_mov_b64 s[34:35], -1
	s_waitcnt vmcnt(4)
	v_lshlrev_b32_e32 v44, 16, v208
	v_and_b32_e32 v45, 0xffff0000, v208
	v_lshlrev_b32_e32 v40, 16, v209
	v_and_b32_e32 v41, 0xffff0000, v209
	v_lshlrev_b32_e32 v46, 16, v210
	v_and_b32_e32 v47, 0xffff0000, v210
	v_lshlrev_b32_e32 v42, 16, v211
	v_and_b32_e32 v43, 0xffff0000, v211
	v_pk_fma_f32 v[38:39], v[38:39], 0.5, v[40:41] op_sel_hi:[1,0,1]
	v_pk_fma_f32 v[36:37], v[36:37], 0.5, v[44:45] op_sel_hi:[1,0,1]
	v_pk_fma_f32 v[34:35], v[34:35], 0.5, v[42:43] op_sel_hi:[1,0,1]
	v_pk_fma_f32 v[32:33], v[32:33], 0.5, v[46:47] op_sel_hi:[1,0,1]
	s_cbranch_vccnz .LBB0_2114
	global_store_dwordx4 v[50:51], v[36:39], off offset:512
	global_store_dwordx4 v[50:51], v[32:35], off offset:528
	s_cbranch_execz .LBB0_2115

.LBB0_2119:
	v_lshl_add_u64 v[38:39], v[146:147], 0, s[24:25]
	s_waitcnt lgkmcnt(0)
	v_lshl_add_u64 v[32:33], v[38:39], 1, s[60:61]
	s_mov_b64 s[34:35], -1
	s_and_b64 vcc, exec, s[4:5]
	s_waitcnt vmcnt(3)
	v_lshlrev_b32_e32 v40, 16, v212
	v_and_b32_e32 v41, 0xffff0000, v212
	v_lshlrev_b32_e32 v34, 16, v213
	v_and_b32_e32 v35, 0xffff0000, v213
	v_lshlrev_b32_e32 v42, 16, v214
	v_and_b32_e32 v43, 0xffff0000, v214
	v_lshlrev_b32_e32 v36, 16, v215
	v_and_b32_e32 v37, 0xffff0000, v215
	v_pk_fma_f32 v[30:31], v[30:31], 0.5, v[34:35] op_sel_hi:[1,0,1]
	v_pk_fma_f32 v[28:29], v[28:29], 0.5, v[40:41] op_sel_hi:[1,0,1]
	v_pk_fma_f32 v[26:27], v[26:27], 0.5, v[36:37] op_sel_hi:[1,0,1]
	v_pk_fma_f32 v[24:25], v[24:25], 0.5, v[42:43] op_sel_hi:[1,0,1]
	v_lshl_add_u64 v[34:35], v[38:39], 2, s[86:87]
	s_cbranch_vccnz .LBB0_2121
	s_mov_b64 s[34:35], 0
	global_store_dwordx4 v[34:35], v[28:31], off
	global_store_dwordx4 v[34:35], v[24:27], off offset:16

.LBB0_2123:
	s_and_b64 vcc, exec, s[4:5]
	s_mov_b64 s[34:35], -1
	s_waitcnt vmcnt(2)
	v_lshlrev_b32_e32 v28, 16, v216
	v_and_b32_e32 v29, 0xffff0000, v216
	v_lshlrev_b32_e32 v24, 16, v217
	v_and_b32_e32 v25, 0xffff0000, v217
	v_lshlrev_b32_e32 v30, 16, v218
	v_and_b32_e32 v31, 0xffff0000, v218
	v_lshlrev_b32_e32 v26, 16, v219
	v_and_b32_e32 v27, 0xffff0000, v219
	v_pk_fma_f32 v[22:23], v[22:23], 0.5, v[24:25] op_sel_hi:[1,0,1]
	v_pk_fma_f32 v[20:21], v[20:21], 0.5, v[28:29] op_sel_hi:[1,0,1]
	v_pk_fma_f32 v[18:19], v[18:19], 0.5, v[26:27] op_sel_hi:[1,0,1]
	v_pk_fma_f32 v[16:17], v[16:17], 0.5, v[30:31] op_sel_hi:[1,0,1]
	s_cbranch_vccnz .LBB0_2126
	global_store_dwordx4 v[34:35], v[20:23], off offset:512
	global_store_dwordx4 v[34:35], v[16:19], off offset:528
	s_cbranch_execz .LBB0_2127

.LBB0_2131:
	v_lshl_add_u64 v[22:23], v[146:147], 0, s[26:27]
	s_waitcnt lgkmcnt(0)
	v_lshl_add_u64 v[16:17], v[22:23], 1, s[60:61]
	s_mov_b64 s[34:35], -1
	s_and_b64 vcc, exec, s[4:5]
	s_waitcnt vmcnt(1)
	v_lshlrev_b32_e32 v24, 16, v220
	v_and_b32_e32 v25, 0xffff0000, v220
	v_lshlrev_b32_e32 v18, 16, v221
	v_and_b32_e32 v19, 0xffff0000, v221
	v_lshlrev_b32_e32 v26, 16, v222
	v_and_b32_e32 v27, 0xffff0000, v222
	v_lshlrev_b32_e32 v20, 16, v223
	v_and_b32_e32 v21, 0xffff0000, v223
	v_pk_fma_f32 v[14:15], v[14:15], 0.5, v[18:19] op_sel_hi:[1,0,1]
	v_pk_fma_f32 v[12:13], v[12:13], 0.5, v[24:25] op_sel_hi:[1,0,1]
	v_pk_fma_f32 v[10:11], v[10:11], 0.5, v[20:21] op_sel_hi:[1,0,1]
	v_pk_fma_f32 v[8:9], v[8:9], 0.5, v[26:27] op_sel_hi:[1,0,1]
	v_lshl_add_u64 v[18:19], v[22:23], 2, s[86:87]
	s_cbranch_vccnz .LBB0_2133
	s_mov_b64 s[34:35], 0
	global_store_dwordx4 v[18:19], v[12:15], off
	global_store_dwordx4 v[18:19], v[8:11], off offset:16

.LBB0_2135:
	s_and_b64 vcc, exec, s[4:5]
	s_mov_b64 s[4:5], -1
	s_waitcnt vmcnt(0)
	v_lshlrev_b32_e32 v12, 16, v224
	v_and_b32_e32 v13, 0xffff0000, v224
	v_lshlrev_b32_e32 v8, 16, v225
	v_and_b32_e32 v9, 0xffff0000, v225
	v_lshlrev_b32_e32 v14, 16, v226
	v_and_b32_e32 v15, 0xffff0000, v226
	v_lshlrev_b32_e32 v10, 16, v227
	v_and_b32_e32 v11, 0xffff0000, v227
	v_pk_fma_f32 v[6:7], v[6:7], 0.5, v[8:9] op_sel_hi:[1,0,1]
	v_pk_fma_f32 v[4:5], v[4:5], 0.5, v[12:13] op_sel_hi:[1,0,1]
	v_pk_fma_f32 v[2:3], v[2:3], 0.5, v[10:11] op_sel_hi:[1,0,1]
	v_pk_fma_f32 v[0:1], v[0:1], 0.5, v[14:15] op_sel_hi:[1,0,1]
	s_cbranch_vccnz .LBB0_2139
	global_store_dwordx4 v[18:19], v[4:7], off offset:512
	global_store_dwordx4 v[18:19], v[0:3], off offset:528
	s_cbranch_execz .LBB0_2140
